# diff attention stagger: priority 1 for the QK/softmax-head segment, 0 for the PV segment (replaces static prio on waves 4-7)
# speedup vs baseline: 1.0171x; 1.0084x over previous
; #define ALDS __attribute__((address_space(3)))
; __device__ __forceinline__ s16x4 vtr(const ALDS unsigned char* p) { return __builtin_bit_cast(s16x4, __builtin_amdgcn_ds_read_tr16_b64_v4i16((ALDS s16x4*)p)); }
; template <int DV, bool BAND> ...
;     ...
;     if (wid >= 4) __builtin_amdgcn_s_setprio(1);
;     int s_cur = 0, s_n2 = 2 * SLOT;
;     for (int t = t0; t < t1; ++t) {
;         asm volatile("s_waitcnt vmcnt(%0)" :: "n"(NP) : "memory");
;         asm volatile("s_waitcnt lgkmcnt(0)\n\ts_barrier" ::: "memory");
;         const int tn = (t + 2 < t1) ? t + 2 : t1 - 1;
;         const ALDS unsigned char* sb = ring + s_cur;
;         f32x16 p0 = negm, p1 = negm;
;         bf16x8 kf[8];
; #pragma unroll
;         for (int d0 = 0; d0 < 4; ++d0) { kf[2 * d0] = *(const ALDS bf16x8*)(sb + ka + d0 * 2048); kf[2 * d0 + 1] = *(const ALDS bf16x8*)(sb + ka + d0 * 2048 + 512); }
;         s16x4 vlo[2][NDB], vhh[2][NDB];
; #pragma unroll
;         for (int db = 0; db < NDB; ++db) { vlo[0][db] = vtr(sb + va[db]); vhh[0][db] = vtr(sb + va[db] + 4 * ROWB); }
; #pragma unroll
;         for (int d0 = 0; d0 < 4; ++d0) {
;             p0 = __builtin_amdgcn_mfma_f32_32x32x16_bf16(kf[2 * d0], qr[d0], p0, 0, 0, 0);
;             p1 = __builtin_amdgcn_mfma_f32_32x32x16_bf16(kf[2 * d0 + 1], qr[d0], p1, 0, 0, 0);
;         }
;         __builtin_amdgcn_sched_barrier(0);
;         ATT_PIECE(0, tn, s_n2); ATT_PIECE(1, tn, s_n2); ATT_PIECE(2, tn, s_n2); ATT_PIECE(3, tn, s_n2);
;         __builtin_amdgcn_sched_barrier(0);
;         if (BAND) {
;             if (t == tq - 2 || t == tq + 2) {
;                 const int rel0 = t * 64 + 8 * hi - qpos;
; #pragma unroll
;                 for (int r = 0; r < 16; ++r) { const int rel = rel0 + 16 * (r >> 3) + (r & 7);
;                     if (rel < -128 || rel > 128) p0[r] = -INFINITY;
;                     if (rel + 32 < -128 || rel + 32 > 128) p1[r] = -INFINITY; }
;             }
;         }
;         float mx = fmaxf(p0[0], p1[0]);
; #pragma unroll
;         for (int r = 1; r < 16; ++r) mx = fmaxf(fmaxf(mx, p0[r]), p1[r]);
;         mx = halfswap_max(mx);
;         const bool first = (!BAND) && (t == t0);
;         const float dl = first ? mx : ((mx > THR) ? mx : 0.f);
;         if (__any(dl != 0.f)) {
;             m += dl;
; #pragma unroll
;             for (int r = 0; r < 16; ++r) { p0[r] -= dl; p1[r] -= dl; negm[r] = -m; }
.LBB0_768:
	v_readlane_b32 s4, v254, 33
	v_readlane_b32 s5, v254, 34
	s_andn2_b64 vcc, exec, s[4:5]
	s_nop 0
	v_cndmask_b32_e64 v3, 0, 1, s[4:5]
	v_cmp_ne_u32_e64 s[40:41], 1, v3
	s_cbranch_vccnz .LBB0_770
	s_waitcnt vmcnt(4)
	s_barrier
.LBB0_770:
	v_lshlrev_b32_e32 v153, 10, v2
	v_lshlrev_b32_e32 v154, 4, v150
	s_waitcnt vmcnt(4)
	v_readlane_b32 s4, v254, 38
	s_waitcnt lgkmcnt(0)
	s_barrier
	s_setprio 1
	s_mov_b32 s62, s48
	s_mov_b32 s63, s48
	v_add3_u32 v12, s4, v153, v154
	ds_read_b128 v[4:7], v12
	ds_read_b128 v[8:11], v12 offset:512
	s_mov_b32 s49, s48
	s_mov_b32 s50, s48
	s_mov_b32 s51, s48
	s_mov_b32 s52, s48
	s_mov_b32 s53, s48
	s_mov_b32 s54, s48
	s_mov_b32 s55, s48
	s_mov_b32 s56, s48
	s_mov_b32 s57, s48
	s_mov_b32 s58, s48
	s_mov_b32 s59, s48
	s_mov_b32 s60, s48
	s_mov_b32 s61, s48
	v_mov_b64_e32 v[82:83], s[62:63]
	v_mov_b64_e32 v[80:81], s[60:61]
	v_mov_b64_e32 v[78:79], s[58:59]
	v_mov_b64_e32 v[76:77], s[56:57]
	v_mov_b64_e32 v[74:75], s[54:55]
	v_mov_b64_e32 v[72:73], s[52:53]
	v_mov_b64_e32 v[70:71], s[50:51]
	v_mov_b64_e32 v[68:69], s[48:49]
	v_bfe_u32 v3, v149, 2, 2
	v_lshrrev_b32_e32 v14, 3, v149
	s_waitcnt vmcnt(3) lgkmcnt(1)
	v_mfma_f32_32x32x16_bf16 v[84:99], v[4:7], v[114:117], v[68:83]
	v_bfe_u32 v15, v149, 1, 1
	v_lshlrev_b32_e32 v2, 11, v2
	v_lshlrev_b32_e32 v13, 8, v3
	v_and_b32_e32 v0, 8, v0
	v_lshlrev_b32_e32 v3, 6, v3
	v_or3_b32 v0, v2, v0, v13
	s_waitcnt lgkmcnt(0)
	v_mfma_f32_32x32x16_bf16 v[68:83], v[8:11], v[114:117], v[68:83]
	ds_read_b128 v[4:7], v12 offset:2048
	ds_read_b128 v[8:11], v12 offset:2560
	ds_read_b128 v[18:21], v12 offset:6656
	s_waitcnt vmcnt(2) lgkmcnt(2)
	v_mfma_f32_32x32x16_bf16 v[84:99], v[4:7], v[118:121], v[84:99]
	ds_read_b128 v[4:7], v12 offset:4096
	s_waitcnt lgkmcnt(2)
	v_mfma_f32_32x32x16_bf16 v[68:83], v[8:11], v[118:121], v[68:83]
	ds_read_b128 v[8:11], v12 offset:4608
	s_waitcnt vmcnt(1) lgkmcnt(1)
	v_mfma_f32_32x32x16_bf16 v[84:99], v[4:7], v[122:125], v[84:99]
	v_and_or_b32 v4, v14, 2, v15
	v_lshlrev_b32_e32 v4, 4, v4
	v_or3_b32 v155, v0, v4, v3
	ds_read_b128 v[2:5], v12 offset:6144
	v_add_u32_e32 v0, 0x4000, v155
	v_xor_b32_e32 v157, 0x80, v0
	v_xor_b32_e32 v156, 64, v0
	s_waitcnt lgkmcnt(1)
	v_mfma_f32_32x32x16_bf16 v[68:83], v[8:11], v[122:125], v[68:83]
	v_xor_b32_e32 v158, 0xc0, v0
	v_add_u32_e32 v108, 0, v155
	v_add_u32_e32 v106, 0, v157
	v_add_u32_e32 v107, 0, v156
	ds_read_b64_tr_b16 v[14:15], v108 offset:16384
	ds_read_b64_tr_b16 v[16:17], v108 offset:17408
	ds_read_b64_tr_b16 v[10:11], v107
	ds_read_b64_tr_b16 v[12:13], v107 offset:1024
	v_add_u32_e32 v67, 0, v158
	s_waitcnt vmcnt(0) lgkmcnt(4)
	v_mfma_f32_32x32x16_bf16 v[84:99], v[2:5], v[126:129], v[84:99]
	ds_read_b64_tr_b16 v[2:3], v106
	ds_read_b64_tr_b16 v[4:5], v106 offset:1024
	ds_read_b64_tr_b16 v[6:7], v67
	ds_read_b64_tr_b16 v[8:9], v67 offset:1024
	v_mfma_f32_32x32x16_bf16 v[68:83], v[18:21], v[126:129], v[68:83]
	s_add_u32 s4, s90, 0x90000
	s_addc_u32 s5, s91, 0
	v_readlane_b32 s7, v254, 39
	s_mov_b32 s6, m0
	s_mov_b32 m0, s7
	s_nop 0
	global_load_lds_dwordx4 v151, s[4:5]
	s_mov_b32 m0, s6
	s_add_u32 s6, s90, 0x90080
	s_addc_u32 s7, s91, 0
	v_readlane_b32 s9, v254, 40
	s_mov_b32 s8, m0
	s_mov_b32 m0, s9
	s_nop 0
	global_load_lds_dwordx4 v151, s[6:7]
	s_mov_b32 m0, s8
	v_readlane_b32 s7, v254, 35
	s_mov_b32 s6, m0
	s_mov_b32 m0, s7
	s_nop 0
	global_load_lds_dwordx4 v152, s[4:5]
	s_mov_b32 m0, s6
	s_add_u32 s4, s90, 0x94800
	s_addc_u32 s5, s91, 0
	v_readlane_b32 s7, v254, 36
	s_mov_b32 s6, m0
	s_mov_b32 m0, s7
	s_nop 0
	global_load_lds_dwordx4 v152, s[4:5]
	s_mov_b32 m0, s6
	s_nop 1
	v_max_f32_e32 v0, v68, v68
	v_max_f32_e32 v18, v84, v84
	v_max_f32_e32 v0, v18, v0
	v_max3_f32 v0, v0, v85, v69
	v_max3_f32 v0, v0, v86, v70
	v_max3_f32 v0, v0, v87, v71
	v_max3_f32 v0, v0, v88, v72
	v_max3_f32 v0, v0, v89, v73
	v_max3_f32 v0, v0, v90, v74
	v_max3_f32 v0, v0, v91, v75
	v_max3_f32 v0, v0, v92, v76
	v_max3_f32 v0, v0, v93, v77
	v_max3_f32 v0, v0, v94, v78
	v_max3_f32 v0, v0, v95, v79
	v_max3_f32 v0, v0, v96, v80
	v_max3_f32 v0, v0, v97, v81
	v_max3_f32 v0, v0, v98, v82
	v_max3_f32 v0, v0, v99, v83
	v_mov_b32_e32 v18, v0
	s_nop 1
	v_permlane32_swap_b32_e32 v0, v18
	v_max_f32_e32 v18, v18, v18
	v_max_f32_e32 v0, v0, v0
	v_max_f32_e32 v0, v0, v18
	v_mov_b32_e32 v159, 0
	v_cmp_neq_f32_e32 vcc, 0, v0
	s_cbranch_vccz .LBB0_772
	v_add_f32_e32 v159, 0, v0
	v_xor_b32_e32 v66, 0x80000000, v159
	v_pk_add_f32 v[84:85], v[84:85], v[0:1] op_sel_hi:[1,0] neg_lo:[0,1] neg_hi:[0,1]
	v_pk_add_f32 v[68:69], v[68:69], v[0:1] op_sel_hi:[1,0] neg_lo:[0,1] neg_hi:[0,1]
	v_pk_add_f32 v[86:87], v[86:87], v[0:1] op_sel_hi:[1,0] neg_lo:[0,1] neg_hi:[0,1]
	v_pk_add_f32 v[70:71], v[70:71], v[0:1] op_sel_hi:[1,0] neg_lo:[0,1] neg_hi:[0,1]
	v_pk_add_f32 v[88:89], v[88:89], v[0:1] op_sel_hi:[1,0] neg_lo:[0,1] neg_hi:[0,1]
	v_pk_add_f32 v[72:73], v[72:73], v[0:1] op_sel_hi:[1,0] neg_lo:[0,1] neg_hi:[0,1]
	v_pk_add_f32 v[90:91], v[90:91], v[0:1] op_sel_hi:[1,0] neg_lo:[0,1] neg_hi:[0,1]
	v_pk_add_f32 v[74:75], v[74:75], v[0:1] op_sel_hi:[1,0] neg_lo:[0,1] neg_hi:[0,1]
	v_pk_add_f32 v[92:93], v[92:93], v[0:1] op_sel_hi:[1,0] neg_lo:[0,1] neg_hi:[0,1]
	v_pk_add_f32 v[76:77], v[76:77], v[0:1] op_sel_hi:[1,0] neg_lo:[0,1] neg_hi:[0,1]
	v_pk_add_f32 v[94:95], v[94:95], v[0:1] op_sel_hi:[1,0] neg_lo:[0,1] neg_hi:[0,1]
	v_pk_add_f32 v[78:79], v[78:79], v[0:1] op_sel_hi:[1,0] neg_lo:[0,1] neg_hi:[0,1]
	v_pk_add_f32 v[96:97], v[96:97], v[0:1] op_sel_hi:[1,0] neg_lo:[0,1] neg_hi:[0,1]
	v_pk_add_f32 v[80:81], v[80:81], v[0:1] op_sel_hi:[1,0] neg_lo:[0,1] neg_hi:[0,1]
	v_pk_add_f32 v[98:99], v[98:99], v[0:1] op_sel_hi:[1,0] neg_lo:[0,1] neg_hi:[0,1]
	v_pk_add_f32 v[82:83], v[82:83], v[0:1] op_sel_hi:[1,0] neg_lo:[0,1] neg_hi:[0,1]
	s_branch .LBB0_773

; __device__ __forceinline__ s16x4 vtr(const ALDS unsigned char* p) { return __builtin_bit_cast(s16x4, __builtin_amdgcn_ds_read_tr16_b64_v4i16((ALDS s16x4*)p)); }
; template <int DV, bool BAND> ...
;     ...
;         float ssum = 0.f;
;         bf16x8 pfs[4];
;     ...
;         ATT_EXP_SLICE(p0, 0, pfs[0]);
; #pragma unroll
;         for (int ks = 0; ks < 4; ++ks) {
;             if (ks + 1 < 4) {
; #pragma unroll
;                 for (int db = 0; db < NDB; ++db) { vlo[(ks + 1) & 1][db] = vtr(sb + va[db] + (ks + 1) * (16 * ROWB)); vhh[(ks + 1) & 1][db] = vtr(sb + va[db] + (ks + 1) * (16 * ROWB) + 4 * ROWB); }
;             }
; #pragma unroll
;             for (int db = 0; db < NDB; ++db) {
;                 const s16x4 lo = vlo[ks & 1][db], hh = vhh[ks & 1][db];
;                 const bf16x8 vf = (bf16x8){lo[0], lo[1], lo[2], lo[3], hh[0], hh[1], hh[2], hh[3]};
;                 o[db] = __builtin_amdgcn_mfma_f32_32x32x16_bf16(vf, pfs[ks], o[db], 0, 0, 0);
;             }
;             if (ks == 0) ATT_EXP_SLICE(p0, 8, pfs[1]);
;             if (ks == 1) ATT_EXP_SLICE(p1, 0, pfs[2]);
;             if (ks == 2) ATT_EXP_SLICE(p1, 8, pfs[3]);
;         }
;     ...
;         l += ssum;
.LBB0_773:
	v_exp_f32_e32 v101, v84
	v_exp_f32_e32 v103, v85
	v_exp_f32_e32 v85, v86
	v_exp_f32_e32 v87, v87
	v_exp_f32_e32 v100, v88
	v_exp_f32_e32 v102, v89
	v_exp_f32_e32 v84, v90
	v_exp_f32_e32 v86, v91
	v_cvt_pk_bf16_f32 v88, v101, v103
	v_cvt_pk_bf16_f32 v89, v85, v87
	v_cvt_pk_bf16_f32 v90, v100, v102
	v_cvt_pk_bf16_f32 v91, v84, v86
	ds_read_b64_tr_b16 v[110:111], v108 offset:20480
	ds_read_b64_tr_b16 v[112:113], v108 offset:21504
	ds_read_b64_tr_b16 v[130:131], v107 offset:4096
	ds_read_b64_tr_b16 v[132:133], v107 offset:5120
	ds_read_b64_tr_b16 v[134:135], v106 offset:4096
	ds_read_b64_tr_b16 v[136:137], v106 offset:5120
	ds_read_b64_tr_b16 v[138:139], v67 offset:4096
	ds_read_b64_tr_b16 v[140:141], v67 offset:5120
	s_waitcnt vmcnt(4)
	s_barrier
	s_setprio 0
	s_waitcnt lgkmcnt(14)
	v_mfma_f32_32x32x16_bf16 v[50:65], v[14:17], v[88:91], 0
	v_exp_f32_e32 v105, v92
	v_exp_f32_e32 v93, v93
	v_exp_f32_e32 v104, v94
	v_exp_f32_e32 v92, v95
	ds_read_b64_tr_b16 v[142:143], v108 offset:24576
	ds_read_b64_tr_b16 v[144:145], v108 offset:25600
	ds_read_b64_tr_b16 v[160:161], v107 offset:8192
	ds_read_b64_tr_b16 v[162:163], v107 offset:9216
	ds_read_b64_tr_b16 v[164:165], v106 offset:8192
	ds_read_b64_tr_b16 v[166:167], v106 offset:9216
	ds_read_b64_tr_b16 v[168:169], v67 offset:8192
	ds_read_b64_tr_b16 v[170:171], v67 offset:9216
	v_cvt_pk_bf16_f32 v94, v105, v93
	v_exp_f32_e32 v0, v76
	s_waitcnt lgkmcnt(14)
	v_mfma_f32_32x32x16_bf16 v[34:49], v[10:13], v[88:91], 0
	v_cvt_pk_bf16_f32 v95, v104, v92
	v_exp_f32_e32 v76, v77
	v_exp_f32_e32 v78, v78
	v_exp_f32_e32 v80, v80
	v_exp_f32_e32 v82, v82
	s_mov_b32 s4, 1
	s_mov_b32 s5, 0x18000
	v_mfma_f32_32x32x16_bf16 v[18:33], v[2:5], v[88:91], 0
	s_mov_b32 s6, 0x8000
	s_movk_i32 s49, 0x900
	v_mfma_f32_32x32x16_bf16 v[2:17], v[6:9], v[88:91], 0
	v_exp_f32_e32 v89, v96
	v_exp_f32_e32 v91, v97
	v_exp_f32_e32 v88, v98
	v_exp_f32_e32 v90, v99
	v_exp_f32_e32 v99, v68
	v_cvt_pk_bf16_f32 v96, v89, v91
	v_exp_f32_e32 v98, v79
	v_cvt_pk_bf16_f32 v97, v88, v90
	s_nop 1
	v_mfma_f32_32x32x16_bf16 v[50:65], v[110:113], v[94:97], v[50:65]
	v_exp_f32_e32 v113, v69
	v_exp_f32_e32 v112, v83
	v_cvt_pk_bf16_f32 v68, v99, v113
	s_waitcnt lgkmcnt(12)
	v_mfma_f32_32x32x16_bf16 v[34:49], v[130:133], v[94:97], v[34:49]
	s_waitcnt lgkmcnt(10)
	v_mfma_f32_32x32x16_bf16 v[18:33], v[134:137], v[94:97], v[18:33]
	v_exp_f32_e32 v134, v70
	v_exp_f32_e32 v135, v71
	v_exp_f32_e32 v136, v72
	v_exp_f32_e32 v137, v73
	v_cvt_pk_bf16_f32 v69, v134, v135
	v_cvt_pk_bf16_f32 v70, v136, v137
	s_waitcnt lgkmcnt(8)
	v_mfma_f32_32x32x16_bf16 v[2:17], v[138:141], v[94:97], v[2:17]
	v_exp_f32_e32 v138, v74
	v_exp_f32_e32 v139, v75
	ds_read_b64_tr_b16 v[72:73], v108 offset:28672
	ds_read_b64_tr_b16 v[74:75], v108 offset:29696
	ds_read_b64_tr_b16 v[94:95], v107 offset:12288
	ds_read_b64_tr_b16 v[96:97], v107 offset:13312
	ds_read_b64_tr_b16 v[108:109], v106 offset:12288
	ds_read_b64_tr_b16 v[110:111], v106 offset:13312
	ds_read_b64_tr_b16 v[130:131], v67 offset:12288
	ds_read_b64_tr_b16 v[132:133], v67 offset:13312
	v_exp_f32_e32 v106, v81
	v_add_f32_e32 v81, v113, v99
	v_cvt_pk_bf16_f32 v71, v138, v139
	v_add_f32_e32 v107, v135, v134
	v_add_f32_e32 v83, v137, v136
	s_waitcnt lgkmcnt(14)
	v_mfma_f32_32x32x16_bf16 v[50:65], v[142:145], v[68:71], v[50:65]
	v_add_f32_e32 v113, v139, v138
	v_mov_b32_e32 v67, v66
	s_waitcnt lgkmcnt(12)
	v_mfma_f32_32x32x16_bf16 v[34:49], v[160:163], v[68:71], v[34:49]
	s_waitcnt lgkmcnt(10)
	v_mfma_f32_32x32x16_bf16 v[18:33], v[164:167], v[68:71], v[18:33]
	s_waitcnt lgkmcnt(8)
	v_mfma_f32_32x32x16_bf16 v[2:17], v[168:171], v[68:71], v[2:17]
	v_cvt_pk_bf16_f32 v68, v0, v76
	v_cvt_pk_bf16_f32 v69, v78, v98
	v_cvt_pk_bf16_f32 v70, v80, v106
	v_cvt_pk_bf16_f32 v71, v82, v112
	s_waitcnt lgkmcnt(6)
	s_nop 0
	v_mfma_f32_32x32x16_bf16 v[50:65], v[72:75], v[68:71], v[50:65]
	v_add_f32_e64 v72, v102, v100
	v_add_f32_e64 v73, v103, v101
	v_add_f32_e64 v74, v86, v84
	v_add_f32_e64 v75, v87, v85
	v_add_f32_e64 v72, v74, v72
	v_add_f32_e64 v73, v75, v73
	v_pk_add_f32 v[74:75], v[106:107], v[80:81]
	v_pk_add_f32 v[72:73], v[72:73], v[72:73] op_sel_hi:[0,1]
	v_mov_b32_e32 v77, v73
	s_waitcnt lgkmcnt(4)
	v_mfma_f32_32x32x16_bf16 v[34:49], v[94:97], v[68:71], v[34:49]
	v_add_f32_e64 v80, v112, v82
	v_add_f32_e64 v81, v113, v83
	v_mov_b32_e32 v72, v66
	v_add_f32_e64 v74, v80, v74
	v_add_f32_e64 v75, v81, v75
	v_mov_b32_e32 v73, v66
	v_mov_b32_e32 v80, v66
	v_mov_b32_e32 v81, v66
	s_waitcnt lgkmcnt(2)
	v_mfma_f32_32x32x16_bf16 v[18:33], v[108:111], v[68:71], v[18:33]
	s_waitcnt lgkmcnt(0)
	v_mfma_f32_32x32x16_bf16 v[2:17], v[130:133], v[68:71], v[2:17]
	v_add_f32_e64 v68, v92, v104
	v_add_f32_e64 v69, v93, v105
	v_add_f32_e64 v70, v90, v88
	v_add_f32_e64 v71, v91, v89
	v_pk_add_f32 v[68:69], v[68:69], v[68:69] op_sel_hi:[0,1]
	v_pk_add_f32 v[70:71], v[70:71], v[70:71] op_sel_hi:[0,1]
	v_mov_b32_e32 v99, v71
	v_mov_b32_e32 v79, v69
	v_pk_add_f32 v[68:69], v[98:99], v[78:79]
	v_pk_add_f32 v[70:71], v[76:77], v[0:1]
	v_mov_b32_e32 v76, v66
	v_pk_add_f32 v[68:69], v[68:69], v[70:71]
	v_mov_b32_e32 v70, v66
	v_pk_add_f32 v[68:69], v[74:75], v[68:69]
	v_mov_b32_e32 v71, v66
	v_add_f32_e32 v160, v68, v69
	v_mov_b32_e32 v68, v66
	v_mov_b32_e32 v69, v66
	v_mov_b32_e32 v74, v66
	v_mov_b32_e32 v75, v66
	v_mov_b32_e32 v77, v66
	v_mov_b32_e32 v78, v66
	v_mov_b32_e32 v79, v66
	s_branch .LBB0_775
; __device__ __forceinline__ s16x4 vtr(const ALDS unsigned char* p) { return __builtin_bit_cast(s16x4, __builtin_amdgcn_ds_read_tr16_b64_v4i16((ALDS s16x4*)p)); }
; template <int DV, bool BAND> ...
;     ...
;         float ssum = 0.f;
;         bf16x8 pfs[4];
;     ...
;         ATT_EXP_SLICE(p0, 0, pfs[0]);
; #pragma unroll
;         for (int ks = 0; ks < 4; ++ks) {
;             if (ks + 1 < 4) {
; #pragma unroll
;                 for (int db = 0; db < NDB; ++db) { vlo[(ks + 1) & 1][db] = vtr(sb + va[db] + (ks + 1) * (16 * ROWB)); vhh[(ks + 1) & 1][db] = vtr(sb + va[db] + (ks + 1) * (16 * ROWB) + 4 * ROWB); }
;             }
; #pragma unroll
;             for (int db = 0; db < NDB; ++db) {
;                 const s16x4 lo = vlo[ks & 1][db], hh = vhh[ks & 1][db];
;                 const bf16x8 vf = (bf16x8){lo[0], lo[1], lo[2], lo[3], hh[0], hh[1], hh[2], hh[3]};
;                 o[db] = __builtin_amdgcn_mfma_f32_32x32x16_bf16(vf, pfs[ks], o[db], 0, 0, 0);
;             }
;             if (ks == 0) ATT_EXP_SLICE(p0, 8, pfs[1]);
;             if (ks == 1) ATT_EXP_SLICE(p1, 0, pfs[2]);
;             if (ks == 2) ATT_EXP_SLICE(p1, 8, pfs[3]);
;         }
;     ...
;         l += ssum;
;         s_cur = (s_cur == 2 * SLOT) ? 0 : s_cur + SLOT; s_n2 = (s_n2 == 2 * SLOT) ? 0 : s_n2 + SLOT;
.LBB0_774:
	v_exp_f32_e32 v167, v98
	v_exp_f32_e32 v169, v99
	v_exp_f32_e32 v171, v100
	v_exp_f32_e32 v173, v101
	v_exp_f32_e32 v166, v102
	v_exp_f32_e32 v168, v103
	v_exp_f32_e32 v170, v104
	v_exp_f32_e32 v172, v105
	v_cvt_pk_bf16_f32 v98, v167, v169
	v_cvt_pk_bf16_f32 v99, v171, v173
	v_cvt_pk_bf16_f32 v100, v166, v168
	v_cvt_pk_bf16_f32 v101, v170, v172
	ds_read_b64_tr_b16 v[102:103], v164 offset:20480
	ds_read_b64_tr_b16 v[104:105], v164 offset:21504
	s_waitcnt vmcnt(4)
	s_barrier
	s_setprio 0
	s_waitcnt lgkmcnt(8)
	v_mfma_f32_32x32x16_bf16 v[50:65], v[142:145], v[98:101], v[50:65]
	v_exp_f32_e32 v142, v82
	v_exp_f32_e32 v143, v83
	v_exp_f32_e32 v144, v84
	v_exp_f32_e32 v145, v85
	v_exp_f32_e32 v165, v86
	v_exp_f32_e32 v174, v87
	v_exp_f32_e32 v175, v88
	s_waitcnt lgkmcnt(6)
	v_mfma_f32_32x32x16_bf16 v[34:49], v[138:141], v[98:101], v[34:49]
	v_exp_f32_e32 v139, v110
	v_exp_f32_e32 v141, v111
	v_exp_f32_e32 v138, v112
	v_exp_f32_e32 v140, v113
	v_exp_f32_e32 v176, v89
	v_cvt_pk_bf16_f32 v86, v142, v143
	v_cvt_pk_bf16_f32 v87, v144, v145
	s_waitcnt lgkmcnt(4)
	v_mfma_f32_32x32x16_bf16 v[18:33], v[134:137], v[98:101], v[18:33]
	v_exp_f32_e32 v135, v106
	v_exp_f32_e32 v137, v107
	v_exp_f32_e32 v134, v108
	v_exp_f32_e32 v136, v109
	ds_read_b64_tr_b16 v[106:107], v164 offset:24576
	ds_read_b64_tr_b16 v[108:109], v164 offset:25600
	v_cvt_pk_bf16_f32 v88, v165, v174
	v_cvt_pk_bf16_f32 v89, v175, v176
	s_waitcnt lgkmcnt(4)
	v_mfma_f32_32x32x16_bf16 v[2:17], v[130:133], v[98:101], v[2:17]
	v_cvt_pk_bf16_f32 v98, v135, v137
	v_cvt_pk_bf16_f32 v99, v134, v136
	v_cvt_pk_bf16_f32 v100, v139, v141
	v_cvt_pk_bf16_f32 v101, v138, v140
	v_add_f32_e64 v82, v168, v166
	v_add_f32_e64 v83, v169, v167
	v_exp_f32_e32 v0, v90
	v_exp_f32_e32 v90, v94
	s_waitcnt lgkmcnt(2)
	v_mfma_f32_32x32x16_bf16 v[50:65], v[102:105], v[98:101], v[50:65]
	ds_read_b64_tr_b16 v[102:103], v163 offset:4096
	ds_read_b64_tr_b16 v[104:105], v163 offset:5120
	ds_read_b64_tr_b16 v[110:111], v164 offset:29696
	v_exp_f32_e32 v94, v96
	v_exp_f32_e32 v96, v97
	v_add_f32_e32 v97, v176, v175
	s_add_i32 s7, s6, 0x8000
	s_cmp_lg_u32 s6, 0x18000
	s_cselect_b32 s6, s7, 0
	s_waitcnt lgkmcnt(1)
	v_mfma_f32_32x32x16_bf16 v[34:49], v[102:105], v[98:101], v[34:49]
	ds_read_b64_tr_b16 v[102:103], v161 offset:4096
	ds_read_b64_tr_b16 v[104:105], v161 offset:5120
	ds_read_b64_tr_b16 v[130:131], v161 offset:8192
	ds_read_b64_tr_b16 v[132:133], v161 offset:9216
	s_add_i32 s7, s5, 0x8000
	s_cmp_lg_u32 s5, 0x18000
	s_cselect_b32 s5, s7, 0
	s_add_i32 s4, s4, 1
	s_cmp_lg_u32 s4, 64
	s_waitcnt lgkmcnt(2)
	v_mfma_f32_32x32x16_bf16 v[18:33], v[102:105], v[98:101], v[18:33]
	ds_read_b64_tr_b16 v[102:103], v162 offset:4096
	ds_read_b64_tr_b16 v[104:105], v162 offset:5120
	ds_read_b64_tr_b16 v[84:85], v161 offset:13312
	s_waitcnt lgkmcnt(1)
	v_mfma_f32_32x32x16_bf16 v[2:17], v[102:105], v[98:101], v[2:17]
	v_add_f32_e64 v102, v172, v170
	v_add_f32_e64 v103, v173, v171
	v_add_f32_e64 v82, v102, v82
	v_add_f32_e64 v83, v103, v83
	v_mfma_f32_32x32x16_bf16 v[50:65], v[106:109], v[86:89], v[50:65]
	ds_read_b64_tr_b16 v[98:99], v163 offset:8192
	ds_read_b64_tr_b16 v[100:101], v163 offset:9216
	ds_read_b64_tr_b16 v[108:109], v164 offset:28672
	ds_read_b64_tr_b16 v[102:103], v163 offset:12288
	ds_read_b64_tr_b16 v[104:105], v163 offset:13312
	v_pk_add_f32 v[106:107], v[82:83], v[82:83] op_sel_hi:[0,1]
	v_pk_add_f32 v[82:83], v[136:137], v[134:135]
	v_exp_f32_e32 v106, v91
	v_pk_add_f32 v[112:113], v[82:83], v[82:83] op_sel_hi:[0,1]
	v_pk_add_f32 v[82:83], v[140:141], v[138:139]
	s_waitcnt lgkmcnt(3)
	v_mfma_f32_32x32x16_bf16 v[34:49], v[98:101], v[86:89], v[34:49]
	ds_read_b64_tr_b16 v[98:99], v162 offset:8192
	ds_read_b64_tr_b16 v[100:101], v162 offset:9216
	v_add_f32_e64 v134, v82, v82
	v_add_f32_e64 v135, v82, v83
	v_exp_f32_e32 v112, v92
	v_exp_f32_e32 v134, v93
	v_exp_f32_e32 v92, v95
	v_add_f32_e32 v91, v143, v142
	v_add_f32_e32 v93, v145, v144
	v_mfma_f32_32x32x16_bf16 v[18:33], v[130:133], v[86:89], v[18:33]
	ds_read_b64_tr_b16 v[130:131], v162 offset:12288
	ds_read_b64_tr_b16 v[132:133], v162 offset:13312
	ds_read_b64_tr_b16 v[82:83], v161 offset:12288
	v_add_f32_e32 v95, v174, v165
	s_waitcnt lgkmcnt(3)
	v_mfma_f32_32x32x16_bf16 v[2:17], v[98:101], v[86:89], v[2:17]
	v_cvt_pk_bf16_f32 v86, v0, v106
	v_cvt_pk_bf16_f32 v87, v112, v134
	v_cvt_pk_bf16_f32 v88, v90, v92
	v_cvt_pk_bf16_f32 v89, v94, v96
	v_add_f32_e64 v98, v106, v0
	v_add_f32_e64 v99, v107, v1
	v_pk_add_f32 v[100:101], v[134:135], v[112:113]
	v_pk_add_f32 v[90:91], v[92:93], v[90:91]
	v_mfma_f32_32x32x16_bf16 v[50:65], v[108:111], v[86:89], v[50:65]
	v_add_f32_e64 v92, v96, v94
	v_add_f32_e64 v93, v97, v95
	v_add_f32_e64 v98, v100, v98
	v_add_f32_e64 v99, v101, v99
	v_add_f32_e64 v90, v92, v90
	v_add_f32_e64 v91, v93, v91
	v_pk_add_f32 v[90:91], v[90:91], v[98:99]
	s_nop 0
	v_add_f32_e32 v0, v90, v91
	v_mfma_f32_32x32x16_bf16 v[34:49], v[102:105], v[86:89], v[34:49]
	v_add_f32_e32 v160, v160, v0
	s_waitcnt lgkmcnt(0)
	v_mfma_f32_32x32x16_bf16 v[18:33], v[82:85], v[86:89], v[18:33]
	v_mfma_f32_32x32x16_bf16 v[2:17], v[130:133], v[86:89], v[2:17]
	s_cbranch_scc0 .LBB0_777
; #define ALDS __attribute__((address_space(3)))
; __device__ __forceinline__ s16x4 vtr(const ALDS unsigned char* p) { return __builtin_bit_cast(s16x4, __builtin_amdgcn_ds_read_tr16_b64_v4i16((ALDS s16x4*)p)); }
; __device__ __forceinline__ float halfswap_max(float v) { auto rr = __builtin_amdgcn_permlane32_swap(__float_as_uint(v), __float_as_uint(v), false, false); return fmaxf(__uint_as_float(rr[0]), __uint_as_float(rr[1])); }
; template <int DV, bool BAND> ...
;     ...
;     for (int t = t0; t < t1; ++t) {
;         asm volatile("s_waitcnt vmcnt(%0)" :: "n"(NP) : "memory");
;         asm volatile("s_waitcnt lgkmcnt(0)\n\ts_barrier" ::: "memory");
;         const int tn = (t + 2 < t1) ? t + 2 : t1 - 1;
;         const ALDS unsigned char* sb = ring + s_cur;
;         f32x16 p0 = negm, p1 = negm;
;         bf16x8 kf[8];
; #pragma unroll
;         for (int d0 = 0; d0 < 4; ++d0) { kf[2 * d0] = *(const ALDS bf16x8*)(sb + ka + d0 * 2048); kf[2 * d0 + 1] = *(const ALDS bf16x8*)(sb + ka + d0 * 2048 + 512); }
;         s16x4 vlo[2][NDB], vhh[2][NDB];
; #pragma unroll
;         for (int db = 0; db < NDB; ++db) { vlo[0][db] = vtr(sb + va[db]); vhh[0][db] = vtr(sb + va[db] + 4 * ROWB); }
; #pragma unroll
;         for (int d0 = 0; d0 < 4; ++d0) {
;             p0 = __builtin_amdgcn_mfma_f32_32x32x16_bf16(kf[2 * d0], qr[d0], p0, 0, 0, 0);
;             p1 = __builtin_amdgcn_mfma_f32_32x32x16_bf16(kf[2 * d0 + 1], qr[d0], p1, 0, 0, 0);
;         }
;         __builtin_amdgcn_sched_barrier(0);
;         ATT_PIECE(0, tn, s_n2); ATT_PIECE(1, tn, s_n2); ATT_PIECE(2, tn, s_n2); ATT_PIECE(3, tn, s_n2);
;         __builtin_amdgcn_sched_barrier(0);
;         if (BAND) {
;             if (t == tq - 2 || t == tq + 2) {
;                 const int rel0 = t * 64 + 8 * hi - qpos;
; #pragma unroll
;                 for (int r = 0; r < 16; ++r) { const int rel = rel0 + 16 * (r >> 3) + (r & 7);
;                     if (rel < -128 || rel > 128) p0[r] = -INFINITY;
;                     if (rel + 32 < -128 || rel + 32 > 128) p1[r] = -INFINITY; }
;             }
;         }
;         float mx = fmaxf(p0[0], p1[0]);
; #pragma unroll
;         for (int r = 1; r < 16; ++r) mx = fmaxf(fmaxf(mx, p0[r]), p1[r]);
;         mx = halfswap_max(mx);
;         const bool first = (!BAND) && (t == t0);
;         const float dl = first ? mx : ((mx > THR) ? mx : 0.f);
;         if (__any(dl != 0.f)) {
.LBB0_775:
	s_add_i32 s7, s6, 0
	s_waitcnt vmcnt(4)
	s_add_i32 s8, s7, s67
	s_waitcnt lgkmcnt(0)
	s_barrier
	s_setprio 1
	v_add3_u32 v0, s8, v153, v154
	ds_read_b128 v[82:85], v0
	ds_read_b128 v[130:133], v0 offset:512
	v_add_u32_e32 v164, s7, v155
	s_waitcnt lgkmcnt(1)
	v_mfma_f32_32x32x16_bf16 v[98:113], v[82:85], v[114:117], v[66:81]
	v_mov_b64_e32 v[96:97], v[80:81]
	v_mov_b64_e32 v[94:95], v[78:79]
	v_mov_b64_e32 v[92:93], v[76:77]
	v_mov_b64_e32 v[90:91], v[74:75]
	v_mov_b64_e32 v[88:89], v[72:73]
	v_mov_b64_e32 v[86:87], v[70:71]
	v_mov_b64_e32 v[84:85], v[68:69]
	v_mov_b64_e32 v[82:83], v[66:67]
	v_add_u32_e32 v161, s7, v157
	v_add_u32_e32 v163, s7, v156
	s_waitcnt lgkmcnt(0)
	v_mfma_f32_32x32x16_bf16 v[82:97], v[130:133], v[114:117], v[82:97]
	ds_read_b128 v[130:133], v0 offset:2048
	ds_read_b128 v[134:137], v0 offset:2560
	v_add_u32_e32 v162, s7, v158
	s_min_u32 s7, s4, 61
	s_waitcnt lgkmcnt(1)
	v_mfma_f32_32x32x16_bf16 v[98:113], v[130:133], v[118:121], v[98:113]
	s_waitcnt lgkmcnt(0)
	v_mfma_f32_32x32x16_bf16 v[82:97], v[134:137], v[118:121], v[82:97]
	ds_read_b128 v[130:133], v0 offset:4096
	ds_read_b128 v[134:137], v0 offset:4608
	ds_read_b128 v[166:169], v0 offset:6656
	s_waitcnt lgkmcnt(2)
	v_mfma_f32_32x32x16_bf16 v[98:113], v[130:133], v[122:125], v[98:113]
	ds_read_b128 v[130:133], v0 offset:6144
	ds_read_b64_tr_b16 v[142:143], v164 offset:16384
	ds_read_b64_tr_b16 v[144:145], v164 offset:17408
	ds_read_b64_tr_b16 v[138:139], v163
	ds_read_b64_tr_b16 v[140:141], v163 offset:1024
	s_waitcnt lgkmcnt(6)
	v_mfma_f32_32x32x16_bf16 v[82:97], v[134:137], v[122:125], v[82:97]
	s_waitcnt lgkmcnt(4)
	v_mfma_f32_32x32x16_bf16 v[98:113], v[130:133], v[126:129], v[98:113]
	ds_read_b64_tr_b16 v[134:135], v161
	ds_read_b64_tr_b16 v[136:137], v161 offset:1024
	ds_read_b64_tr_b16 v[130:131], v162
	ds_read_b64_tr_b16 v[132:133], v162 offset:1024
	v_mfma_f32_32x32x16_bf16 v[82:97], v[166:169], v[126:129], v[82:97]
	s_mul_i32 s7, s7, 0x48000
	s_add_u32 s7, s90, s7
	s_addc_u32 s12, s91, 0
	s_add_u32 s8, s7, 0x90000
	s_addc_u32 s9, s12, 0
	s_add_i32 s13, s5, s30
	s_mov_b32 s10, m0
	s_mov_b32 m0, s13
	s_nop 0
	global_load_lds_dwordx4 v151, s[8:9]
	s_mov_b32 m0, s10
	s_add_u32 s10, s7, 0x90080
	s_addc_u32 s11, s12, 0
	s_addk_i32 s13, 0x2000
	s_mov_b32 s14, m0
	s_mov_b32 m0, s13
	s_nop 0
	global_load_lds_dwordx4 v151, s[10:11]
	s_mov_b32 m0, s14
	s_add_i32 s10, s5, s84
	s_mov_b32 s11, m0
	s_mov_b32 m0, s10
	s_nop 0
	global_load_lds_dwordx4 v152, s[8:9]
	s_mov_b32 m0, s11
	s_add_u32 s8, s7, 0x94800
	s_addc_u32 s9, s12, 0
	s_addk_i32 s10, 0x400
	s_mov_b32 s7, m0
	s_mov_b32 m0, s10
	s_nop 0
	global_load_lds_dwordx4 v152, s[8:9]
	s_mov_b32 m0, s7
	v_max_f32_e32 v0, v82, v82
	v_max_f32_e32 v165, v98, v98
	v_max_f32_e32 v0, v165, v0
	v_max3_f32 v0, v0, v99, v83
	v_max3_f32 v0, v0, v100, v84
	v_max3_f32 v0, v0, v101, v85
	v_max3_f32 v0, v0, v102, v86
	v_max3_f32 v0, v0, v103, v87
	v_max3_f32 v0, v0, v104, v88
	v_max3_f32 v0, v0, v105, v89
	v_max3_f32 v0, v0, v106, v90
	v_max3_f32 v0, v0, v107, v91
	v_max3_f32 v0, v0, v108, v92
	v_max3_f32 v0, v0, v109, v93
	v_max3_f32 v0, v0, v110, v94
	v_max3_f32 v0, v0, v111, v95
	v_max3_f32 v0, v0, v112, v96
	v_max3_f32 v0, v0, v113, v97
	v_mov_b32_e32 v165, v0
	s_nop 1
	v_permlane32_swap_b32_e32 v0, v165
	v_max_f32_e32 v165, v165, v165
	v_max_f32_e32 v0, v0, v0
	v_max_f32_e32 v0, v0, v165
	v_cmp_lt_f32_e32 vcc, s31, v0
	s_nop 1
	v_cndmask_b32_e32 v0, 0, v0, vcc
	v_cmp_neq_f32_e32 vcc, 0, v0
	s_cbranch_vccz .LBB0_774
; template <int DV, bool BAND> ...
;     ...
;         if (__any(dl != 0.f)) {
;             m += dl;
; #pragma unroll
;             for (int r = 0; r < 16; ++r) { p0[r] -= dl; p1[r] -= dl; negm[r] = -m; }
;             const float f = first ? 1.f : __builtin_amdgcn_exp2f(-dl);
;             l *= f;
; #pragma unroll
;             for (int db = 0; db < NDB; ++db)
; #pragma unroll
;                 for (int r = 0; r < 16; ++r) o[db][r] *= f;
;         }
	v_exp_f32_e64 v68, -v0
	v_add_f32_e32 v159, v159, v0
	v_xor_b32_e32 v66, 0x80000000, v159
	v_pk_add_f32 v[98:99], v[98:99], v[0:1] op_sel_hi:[1,0] neg_lo:[0,1] neg_hi:[0,1]
	v_pk_add_f32 v[82:83], v[82:83], v[0:1] op_sel_hi:[1,0] neg_lo:[0,1] neg_hi:[0,1]
	v_pk_add_f32 v[100:101], v[100:101], v[0:1] op_sel_hi:[1,0] neg_lo:[0,1] neg_hi:[0,1]
	v_pk_add_f32 v[84:85], v[84:85], v[0:1] op_sel_hi:[1,0] neg_lo:[0,1] neg_hi:[0,1]
	v_pk_add_f32 v[102:103], v[102:103], v[0:1] op_sel_hi:[1,0] neg_lo:[0,1] neg_hi:[0,1]
	v_pk_add_f32 v[86:87], v[86:87], v[0:1] op_sel_hi:[1,0] neg_lo:[0,1] neg_hi:[0,1]
	v_pk_add_f32 v[104:105], v[104:105], v[0:1] op_sel_hi:[1,0] neg_lo:[0,1] neg_hi:[0,1]
	v_pk_add_f32 v[88:89], v[88:89], v[0:1] op_sel_hi:[1,0] neg_lo:[0,1] neg_hi:[0,1]
	v_pk_add_f32 v[106:107], v[106:107], v[0:1] op_sel_hi:[1,0] neg_lo:[0,1] neg_hi:[0,1]
	v_pk_add_f32 v[90:91], v[90:91], v[0:1] op_sel_hi:[1,0] neg_lo:[0,1] neg_hi:[0,1]
	v_pk_add_f32 v[108:109], v[108:109], v[0:1] op_sel_hi:[1,0] neg_lo:[0,1] neg_hi:[0,1]
	v_pk_add_f32 v[92:93], v[92:93], v[0:1] op_sel_hi:[1,0] neg_lo:[0,1] neg_hi:[0,1]
	v_pk_add_f32 v[110:111], v[110:111], v[0:1] op_sel_hi:[1,0] neg_lo:[0,1] neg_hi:[0,1]
	v_pk_add_f32 v[94:95], v[94:95], v[0:1] op_sel_hi:[1,0] neg_lo:[0,1] neg_hi:[0,1]
	v_pk_add_f32 v[112:113], v[112:113], v[0:1] op_sel_hi:[1,0] neg_lo:[0,1] neg_hi:[0,1]
	v_pk_add_f32 v[96:97], v[96:97], v[0:1] op_sel_hi:[1,0] neg_lo:[0,1] neg_hi:[0,1]
	v_pk_mul_f32 v[64:65], v[64:65], v[68:69] op_sel_hi:[1,0]
	v_pk_mul_f32 v[62:63], v[62:63], v[68:69] op_sel_hi:[1,0]
	v_pk_mul_f32 v[60:61], v[60:61], v[68:69] op_sel_hi:[1,0]
	v_pk_mul_f32 v[58:59], v[58:59], v[68:69] op_sel_hi:[1,0]
	v_pk_mul_f32 v[56:57], v[56:57], v[68:69] op_sel_hi:[1,0]
	v_pk_mul_f32 v[54:55], v[54:55], v[68:69] op_sel_hi:[1,0]
	v_pk_mul_f32 v[52:53], v[52:53], v[68:69] op_sel_hi:[1,0]
	v_pk_mul_f32 v[50:51], v[50:51], v[68:69] op_sel_hi:[1,0]
	v_pk_mul_f32 v[48:49], v[48:49], v[68:69] op_sel_hi:[1,0]
	v_pk_mul_f32 v[46:47], v[46:47], v[68:69] op_sel_hi:[1,0]
	v_pk_mul_f32 v[44:45], v[44:45], v[68:69] op_sel_hi:[1,0]
	v_pk_mul_f32 v[42:43], v[42:43], v[68:69] op_sel_hi:[1,0]
	v_pk_mul_f32 v[40:41], v[40:41], v[68:69] op_sel_hi:[1,0]
	v_pk_mul_f32 v[38:39], v[38:39], v[68:69] op_sel_hi:[1,0]
	v_pk_mul_f32 v[36:37], v[36:37], v[68:69] op_sel_hi:[1,0]
	v_pk_mul_f32 v[34:35], v[34:35], v[68:69] op_sel_hi:[1,0]
	v_pk_mul_f32 v[32:33], v[32:33], v[68:69] op_sel_hi:[1,0]
	v_pk_mul_f32 v[30:31], v[30:31], v[68:69] op_sel_hi:[1,0]
	v_pk_mul_f32 v[28:29], v[28:29], v[68:69] op_sel_hi:[1,0]
	v_pk_mul_f32 v[26:27], v[26:27], v[68:69] op_sel_hi:[1,0]
	v_pk_mul_f32 v[24:25], v[24:25], v[68:69] op_sel_hi:[1,0]
	v_pk_mul_f32 v[22:23], v[22:23], v[68:69] op_sel_hi:[1,0]
	v_pk_mul_f32 v[20:21], v[20:21], v[68:69] op_sel_hi:[1,0]
	v_pk_mul_f32 v[18:19], v[18:19], v[68:69] op_sel_hi:[1,0]
	v_pk_mul_f32 v[16:17], v[16:17], v[68:69] op_sel_hi:[1,0]
	v_pk_mul_f32 v[14:15], v[14:15], v[68:69] op_sel_hi:[1,0]
	v_pk_mul_f32 v[12:13], v[12:13], v[68:69] op_sel_hi:[1,0]
	v_pk_mul_f32 v[10:11], v[10:11], v[68:69] op_sel_hi:[1,0]
	v_pk_mul_f32 v[8:9], v[8:9], v[68:69] op_sel_hi:[1,0]
	v_pk_mul_f32 v[6:7], v[6:7], v[68:69] op_sel_hi:[1,0]
	v_pk_mul_f32 v[4:5], v[4:5], v[68:69] op_sel_hi:[1,0]
	v_pk_mul_f32 v[2:3], v[2:3], v[68:69] op_sel_hi:[1,0]
	v_mul_f32_e32 v160, v160, v68
	v_mov_b32_e32 v67, v66
	v_mov_b32_e32 v68, v66
	v_mov_b32_e32 v69, v66
	v_mov_b32_e32 v70, v66
	v_mov_b32_e32 v71, v66
	v_mov_b32_e32 v72, v66
	v_mov_b32_e32 v73, v66
	v_mov_b32_e32 v74, v66
	v_mov_b32_e32 v75, v66
	v_mov_b32_e32 v76, v66
	v_mov_b32_e32 v77, v66
	v_mov_b32_e32 v78, v66
	v_mov_b32_e32 v79, v66
	v_mov_b32_e32 v80, v66
	v_mov_b32_e32 v81, v66
	s_branch .LBB0_774
